# GEMM phase start-up: both DMA batches issued before the first wait (vmcnt(2)+barrier moved below the second batch as vmcnt(8))
# speedup vs baseline: 1.0092x; 1.0092x over previous
; #define PG8_STAGE(bufoff, gbase, voff) do { _Pragma("unroll") for (int _i = 0; _i < 2; ++_i) \
;         __builtin_amdgcn_global_load_lds((const unsigned*)((const char*)(gbase) + (voff)[_i]), (PG8_LAS unsigned*)(lds + (bufoff) + ldsw + _i * 8192), 16, 0, 0); } while (0)
; #define PG8_WAIT_V(n) asm volatile("s_waitcnt vmcnt(" #n ")" ::: "memory")
; #define PG8_BAR __builtin_amdgcn_s_barrier()
; template <class Epi, class Sched, bool ALIGN_EPI = false, bool SP2 = false>
; __device__ __forceinline__ void gemm_phase(PG8_LAS unsigned char* lds, const Gemm g, const Sched& S, const Epi& E) {
;     ...
;         PG8_STAGE(PG8_SB(0, 0), cB, voffB); PG8_STAGE(PG8_SB(0, 1), cB + hstep, voffB); PG8_STAGE(PG8_SA(0, 0), cA, voffA); PG8_STAGE(PG8_SA(0, 1), cA + hstep, voffA);
;         if (wr == 1) PG8_BAR;
;         PG8_WAIT_V(2); PG8_BAR;
;         PG8_STAGE(PG8_SB(1, 0), cB + kstep, voffB); PG8_STAGE(PG8_SA(1, 0), cA + kstep, voffA); PG8_STAGE(PG8_SB(1, 1), cB + hstep + kstep, voffB);
;         PG8_WAIT_V(6); PG8_BAR;
.LBB0_170:
	s_lshl_b32 s10, s10, 5
	v_mov_b32_e32 v137, v2
	s_and_b32 s13, s10, 0x60
	s_add_i32 m0, s43, 0x18000
	v_lshl_add_u64 v[4:5], v[4:5], 0, s[28:29]
	v_lshl_add_u64 v[14:15], s[0:1], 0, v[136:137]
	v_mov_b32_e32 v133, v2
	s_lshl_b32 s12, s3, 13
	s_lshl_b32 s14, s13, 7
	global_load_lds_dwordx4 v[4:5], off
	v_lshl_add_u64 v[4:5], v[6:7], 0, s[28:29]
	s_add_i32 m0, s43, 0x1a000
	s_add_i32 s49, s43, 0x8000
	s_add_i32 s50, s43, 0xa000
	v_lshl_add_u64 v[16:17], s[0:1], 0, v[132:133]
	global_load_lds_dwordx4 v[4:5], off
	v_lshl_add_u64 v[4:5], v[14:15], 0, s[28:29]
	s_mov_b32 m0, s49
	s_add_u32 s10, s6, 0x80080
	global_load_lds_dwordx4 v[4:5], off
	v_lshl_add_u64 v[4:5], v[16:17], 0, s[28:29]
	s_mov_b32 m0, s50
	s_addc_u32 s11, s7, 0
	global_load_lds_dwordx4 v[4:5], off
	s_add_i32 m0, s43, 0x1c000
	v_lshl_add_u64 v[4:5], s[10:11], 0, v[134:135]
	global_load_lds_dwordx4 v[4:5], off
	v_lshl_add_u64 v[4:5], s[10:11], 0, v[0:1]
	s_add_i32 m0, s43, 0x1e000
	v_lshrrev_b32_e32 v6, 1, v3
	global_load_lds_dwordx4 v[4:5], off
	v_and_b32_e32 v6, 24, v6
	v_and_b32_e32 v4, 15, v3
	v_lshlrev_b32_e32 v7, 1, v6
	v_lshlrev_b32_e32 v3, 2, v3
	v_lshl_or_b32 v5, s3, 6, v4
	v_lshl_or_b32 v4, v4, 6, v7
	v_and_b32_e32 v3, 32, v3
	v_bitop3_b32 v7, v4, s12, v3 bitop3:0xde
	v_bitop3_b32 v3, v4, s14, v3 bitop3:0xde
	v_lshlrev_b32_e32 v4, 15, v12
	s_cmpk_lt_u32 s2, 0x100
	v_readlane_b32 s2, v250, 59
	v_and_b32_e32 v4, 0xffff0000, v4
	v_lshl_add_u32 v4, v11, 12, v4
	v_add_u32_e32 v152, s2, v5
	v_and_b32_e32 v5, 1, v12
	v_lshl_or_b32 v4, v5, 6, v4
	v_readlane_b32 s2, v247, 10
	v_lshl_add_u32 v4, v13, 1, v4
	v_mov_b32_e32 v5, v2
	v_readlane_b32 s3, v247, 11
	s_waitcnt vmcnt(8)
	s_barrier
	s_waitcnt vmcnt(6)
	v_or_b32_e32 v153, s13, v6
	v_readlane_b32 s12, v247, 14
	v_lshl_add_u64 v[138:139], s[2:3], 0, v[4:5]
	v_lshlrev_b32_e32 v4, 15, v8
	v_and_b32_e32 v4, 0xffff0000, v4
	v_lshl_add_u32 v4, v9, 12, v4
	v_and_b32_e32 v5, 1, v8
	v_lshl_or_b32 v4, v5, 6, v4
	v_lshl_add_u32 v4, v10, 1, v4
	v_mov_b32_e32 v5, v2
	s_cselect_b64 s[10:11], -1, 0
	v_cvt_f32_u32_e32 v188, v173
	v_cvt_f32_u32_e32 v189, v172
	v_fmac_f32_e32 v188, 0x2f800000, v189
	v_fmamk_f32 v188, v188, 0x3a000000, v205
	v_rsq_f32_e32 v240, v188
	v_cvt_f32_u32_e32 v188, v175
	v_cvt_f32_u32_e32 v189, v174
	v_fmac_f32_e32 v188, 0x2f800000, v189
	v_fmamk_f32 v188, v188, 0x3a000000, v205
	v_rsq_f32_e32 v241, v188
	v_cvt_f32_u32_e32 v188, v177
	v_cvt_f32_u32_e32 v189, v176
	v_fmac_f32_e32 v188, 0x2f800000, v189
	v_fmamk_f32 v188, v188, 0x3a000000, v205
	v_rsq_f32_e32 v242, v188
	v_cvt_f32_u32_e32 v188, v179
	v_cvt_f32_u32_e32 v189, v178
	v_fmac_f32_e32 v188, 0x2f800000, v189
	v_fmamk_f32 v188, v188, 0x3a000000, v205
	v_rsq_f32_e32 v243, v188
	v_cvt_f32_u32_e32 v188, v181
	v_cvt_f32_u32_e32 v189, v180
	v_fmac_f32_e32 v188, 0x2f800000, v189
	v_fmamk_f32 v188, v188, 0x3a000000, v205
	v_rsq_f32_e32 v244, v188
	v_cvt_f32_u32_e32 v188, v183
	v_cvt_f32_u32_e32 v189, v182
	v_fmac_f32_e32 v188, 0x2f800000, v189
	v_fmamk_f32 v188, v188, 0x3a000000, v205
	v_rsq_f32_e32 v245, v188
	v_cvt_f32_u32_e32 v188, v185
	v_cvt_f32_u32_e32 v189, v184
	v_fmac_f32_e32 v188, 0x2f800000, v189
	v_fmamk_f32 v188, v188, 0x3a000000, v205
	v_rsq_f32_e32 v246, v188
	v_cvt_f32_u32_e32 v188, v187
	v_cvt_f32_u32_e32 v189, v186
	v_fmac_f32_e32 v188, 0x2f800000, v189
	v_fmamk_f32 v188, v188, 0x3a000000, v205
	v_rsq_f32_e32 v252, v188
	s_nop 0
	v_lshl_add_u64 v[140:141], s[2:3], 0, v[4:5]
	s_mov_b32 s51, 0
	v_add_u32_e32 v154, 0, v7
	v_readlane_b32 s13, v247, 15
	v_readlane_b32 s14, v248, 25
	s_barrier
	v_readlane_b32 s15, v248, 26
	s_branch .LBB0_173

; #define PG8_STAGE(bufoff, gbase, voff) do { _Pragma("unroll") for (int _i = 0; _i < 2; ++_i) \
;         __builtin_amdgcn_global_load_lds((const unsigned*)((const char*)(gbase) + (voff)[_i]), (PG8_LAS unsigned*)(lds + (bufoff) + ldsw + _i * 8192), 16, 0, 0); } while (0)
; #define PG8_WAIT_V(n) asm volatile("s_waitcnt vmcnt(" #n ")" ::: "memory")
; #define PG8_BAR __builtin_amdgcn_s_barrier()
; template <class Epi, class Sched, bool ALIGN_EPI = false, bool SP2 = false>
; __device__ __forceinline__ void gemm_phase(PG8_LAS unsigned char* lds, const Gemm g, const Sched& S, const Epi& E) {
;     ...
;         PG8_STAGE(PG8_SB(0, 0), cB, voffB); PG8_STAGE(PG8_SB(0, 1), cB + hstep, voffB); PG8_STAGE(PG8_SA(0, 0), cA, voffA); PG8_STAGE(PG8_SA(0, 1), cA + hstep, voffA);
;         if (wr == 1) PG8_BAR;
;         PG8_WAIT_V(2); PG8_BAR;
;         PG8_STAGE(PG8_SB(1, 0), cB + kstep, voffB); PG8_STAGE(PG8_SA(1, 0), cA + kstep, voffA); PG8_STAGE(PG8_SB(1, 1), cB + hstep + kstep, voffB);
;         PG8_WAIT_V(6); PG8_BAR;
.LBB0_922:
	v_bfe_u32 v17, v11, 4, 2
	v_and_b32_e32 v16, 15, v11
	v_lshlrev_b32_e32 v19, 4, v17
	v_lshlrev_b32_e32 v11, 2, v11
	s_lshl_b32 s3, s3, 5
	v_mov_b32_e32 v175, v2
	v_lshl_or_b32 v18, s14, 6, v16
	v_lshl_or_b32 v16, v16, 6, v19
	s_lshl_b32 s14, s14, 13
	v_and_b32_e32 v11, 32, v11
	s_and_b32 s3, s3, 0x60
	s_add_i32 m0, s51, 0x18000
	v_lshl_add_u64 v[0:1], v[0:1], 0, s[28:29]
	v_lshl_add_u64 v[12:13], s[88:89], 0, v[174:175]
	v_mov_b32_e32 v159, v2
	v_bitop3_b32 v19, v16, s14, v11 bitop3:0xde
	s_lshl_b32 s14, s3, 7
	global_load_lds_dwordx4 v[0:1], off
	v_lshl_add_u64 v[0:1], v[4:5], 0, s[28:29]
	s_add_i32 m0, s51, 0x1a000
	s_add_i32 s57, s51, 0x8000
	s_add_i32 s58, s51, 0xa000
	v_lshl_add_u64 v[14:15], s[88:89], 0, v[158:159]
	v_bitop3_b32 v192, v16, s14, v11 bitop3:0xde
	global_load_lds_dwordx4 v[0:1], off
	v_lshl_add_u64 v[0:1], v[12:13], 0, s[28:29]
	s_mov_b32 m0, s57
	s_add_u32 s14, s10, 0x80080
	global_load_lds_dwordx4 v[0:1], off
	v_lshl_add_u64 v[0:1], v[14:15], 0, s[28:29]
	s_mov_b32 m0, s58
	s_addc_u32 s15, s11, 0
	global_load_lds_dwordx4 v[0:1], off
	s_add_i32 m0, s51, 0x1c000
	v_lshl_add_u64 v[0:1], s[14:15], 0, v[172:173]
	global_load_lds_dwordx4 v[0:1], off
	v_lshl_add_u64 v[0:1], s[14:15], 0, v[156:157]
	s_add_i32 m0, s51, 0x1e000
	s_cmpk_lt_u32 s2, 0x100
	global_load_lds_dwordx4 v[0:1], off
	v_lshlrev_b32_e32 v0, 15, v9
	v_and_b32_e32 v0, 0xffff0000, v0
	v_readlane_b32 s2, v250, 59
	v_lshl_add_u32 v0, v8, 12, v0
	v_and_b32_e32 v1, 1, v9
	v_add_u32_e32 v193, s2, v18
	v_lshl_or_b32 v194, v17, 3, s3
	v_lshl_or_b32 v0, v1, 6, v0
	v_readlane_b32 s2, v247, 16
	v_lshl_add_u32 v0, v10, 1, v0
	v_mov_b32_e32 v1, v2
	v_readlane_b32 s3, v247, 17
	s_waitcnt vmcnt(8)
	s_barrier
	s_waitcnt vmcnt(6)
	v_readlane_b32 s36, v247, 18
	s_cselect_b64 s[14:15], -1, 0
	v_cvt_f32_u32_e32 v96, v101
	v_cvt_f32_u32_e32 v97, v100
	v_fmac_f32_e32 v96, 0x2f800000, v97
	v_fmamk_f32 v96, v96, 0x3a800000, v205
	v_cvt_f32_u32_e32 v98, v117
	v_cvt_f32_u32_e32 v99, v116
	v_fmac_f32_e32 v98, 0x2f800000, v99
	v_fmamk_f32 v98, v98, 0x3a800000, v205
	v_rsq_f32_e32 v96, v96
	v_sqrt_f32_e32 v97, v98
	v_rsq_f32_e32 v240, v98
	s_nop 0
	v_mul_f32_e32 v160, v96, v97
	v_cvt_f32_u32_e32 v96, v103
	v_cvt_f32_u32_e32 v97, v102
	v_fmac_f32_e32 v96, 0x2f800000, v97
	v_fmamk_f32 v96, v96, 0x3a800000, v205
	v_cvt_f32_u32_e32 v98, v119
	v_cvt_f32_u32_e32 v99, v118
	v_fmac_f32_e32 v98, 0x2f800000, v99
	v_fmamk_f32 v98, v98, 0x3a800000, v205
	v_rsq_f32_e32 v96, v96
	v_sqrt_f32_e32 v97, v98
	v_rsq_f32_e32 v241, v98
	s_nop 0
	v_mul_f32_e32 v161, v96, v97
	v_cvt_f32_u32_e32 v96, v105
	v_cvt_f32_u32_e32 v97, v104
	v_fmac_f32_e32 v96, 0x2f800000, v97
	v_fmamk_f32 v96, v96, 0x3a800000, v205
	v_cvt_f32_u32_e32 v98, v121
	v_cvt_f32_u32_e32 v99, v120
	v_fmac_f32_e32 v98, 0x2f800000, v99
	v_fmamk_f32 v98, v98, 0x3a800000, v205
	v_rsq_f32_e32 v96, v96
	v_sqrt_f32_e32 v97, v98
	v_rsq_f32_e32 v242, v98
	s_nop 0
	v_mul_f32_e32 v162, v96, v97
	v_cvt_f32_u32_e32 v96, v107
	v_cvt_f32_u32_e32 v97, v106
	v_fmac_f32_e32 v96, 0x2f800000, v97
	v_fmamk_f32 v96, v96, 0x3a800000, v205
	v_cvt_f32_u32_e32 v98, v123
	v_cvt_f32_u32_e32 v99, v122
	v_fmac_f32_e32 v98, 0x2f800000, v99
	v_fmamk_f32 v98, v98, 0x3a800000, v205
	v_rsq_f32_e32 v96, v96
	v_sqrt_f32_e32 v97, v98
	v_rsq_f32_e32 v243, v98
	s_nop 0
	v_mul_f32_e32 v163, v96, v97
	v_cvt_f32_u32_e32 v96, v109
	v_cvt_f32_u32_e32 v97, v108
	v_fmac_f32_e32 v96, 0x2f800000, v97
	v_fmamk_f32 v96, v96, 0x3a800000, v205
	v_cvt_f32_u32_e32 v98, v125
	v_cvt_f32_u32_e32 v99, v124
	v_fmac_f32_e32 v98, 0x2f800000, v99
	v_fmamk_f32 v98, v98, 0x3a800000, v205
	v_rsq_f32_e32 v96, v96
	v_sqrt_f32_e32 v97, v98
	v_rsq_f32_e32 v244, v98
	s_nop 0
	v_mul_f32_e32 v164, v96, v97
	v_cvt_f32_u32_e32 v96, v111
	v_cvt_f32_u32_e32 v97, v110
	v_fmac_f32_e32 v96, 0x2f800000, v97
	v_fmamk_f32 v96, v96, 0x3a800000, v205
	v_cvt_f32_u32_e32 v98, v127
	v_cvt_f32_u32_e32 v99, v126
	v_fmac_f32_e32 v98, 0x2f800000, v99
	v_fmamk_f32 v98, v98, 0x3a800000, v205
	v_rsq_f32_e32 v96, v96
	v_sqrt_f32_e32 v97, v98
	v_rsq_f32_e32 v245, v98
	s_nop 0
	v_mul_f32_e32 v165, v96, v97
	v_cvt_f32_u32_e32 v96, v113
	v_cvt_f32_u32_e32 v97, v112
	v_fmac_f32_e32 v96, 0x2f800000, v97
	v_fmamk_f32 v96, v96, 0x3a800000, v205
	v_cvt_f32_u32_e32 v98, v129
	v_cvt_f32_u32_e32 v99, v128
	v_fmac_f32_e32 v98, 0x2f800000, v99
	v_fmamk_f32 v98, v98, 0x3a800000, v205
	v_rsq_f32_e32 v96, v96
	v_sqrt_f32_e32 v97, v98
	v_rsq_f32_e32 v246, v98
	s_nop 0
	v_mul_f32_e32 v166, v96, v97
	v_cvt_f32_u32_e32 v96, v115
	v_cvt_f32_u32_e32 v97, v114
	v_fmac_f32_e32 v96, 0x2f800000, v97
	v_fmamk_f32 v96, v96, 0x3a800000, v205
	v_cvt_f32_u32_e32 v98, v131
	v_cvt_f32_u32_e32 v99, v130
	v_fmac_f32_e32 v98, 0x2f800000, v99
	v_fmamk_f32 v98, v98, 0x3a800000, v205
	v_rsq_f32_e32 v96, v96
	v_sqrt_f32_e32 v97, v98
	v_rsq_f32_e32 v252, v98
	s_nop 0
	v_mul_f32_e32 v167, v96, v97
	v_lshl_add_u64 v[176:177], s[2:3], 0, v[0:1]
	v_lshlrev_b32_e32 v0, 15, v3
	v_and_b32_e32 v0, 0xffff0000, v0
	v_lshl_add_u32 v0, v6, 12, v0
	v_and_b32_e32 v1, 1, v3
	v_lshl_or_b32 v0, v1, 6, v0
	v_lshl_add_u32 v0, v7, 1, v0
	v_mov_b32_e32 v1, v2
	s_mov_b32 s59, 0
	v_cmp_eq_u32_e64 s[40:41], 0, v17
	v_lshl_add_u64 v[178:179], s[2:3], 0, v[0:1]
	v_add_u32_e32 v195, 0, v19
	v_readlane_b32 s37, v247, 19
	v_readlane_b32 s42, v248, 25
	s_barrier
	v_readlane_b32 s43, v248, 26
	s_branch .LBB0_925

; #define PG8_STAGE(bufoff, gbase, voff) do { _Pragma("unroll") for (int _i = 0; _i < 2; ++_i) \
;         __builtin_amdgcn_global_load_lds((const unsigned*)((const char*)(gbase) + (voff)[_i]), (PG8_LAS unsigned*)(lds + (bufoff) + ldsw + _i * 8192), 16, 0, 0); } while (0)
; #define PG8_WAIT_V(n) asm volatile("s_waitcnt vmcnt(" #n ")" ::: "memory")
; #define PG8_BAR __builtin_amdgcn_s_barrier()
; template <class Epi, class Sched, bool ALIGN_EPI = false, bool SP2 = false>
; __device__ __forceinline__ void gemm_phase(PG8_LAS unsigned char* lds, const Gemm g, const Sched& S, const Epi& E) {
;     ...
;         PG8_STAGE(PG8_SB(0, 0), cB, voffB); PG8_STAGE(PG8_SB(0, 1), cB + hstep, voffB); PG8_STAGE(PG8_SA(0, 0), cA, voffA); PG8_STAGE(PG8_SA(0, 1), cA + hstep, voffA);
;         if (wr == 1) PG8_BAR;
;         PG8_WAIT_V(2); PG8_BAR;
;         PG8_STAGE(PG8_SB(1, 0), cB + kstep, voffB); PG8_STAGE(PG8_SA(1, 0), cA + kstep, voffA); PG8_STAGE(PG8_SB(1, 1), cB + hstep + kstep, voffB);
;         PG8_WAIT_V(6); PG8_BAR;
.LBB0_1047:
	v_lshrrev_b32_e32 v20, 1, v3
	v_and_b32_e32 v20, 24, v20
	v_and_b32_e32 v18, 15, v3
	v_lshlrev_b32_e32 v21, 1, v20
	v_lshlrev_b32_e32 v3, 2, v3
	s_lshl_b32 s3, s3, 5
	v_mov_b32_e32 v137, v2
	v_lshl_or_b32 v19, s10, 6, v18
	v_lshl_or_b32 v18, v18, 6, v21
	s_lshl_b32 s10, s10, 13
	v_and_b32_e32 v3, 32, v3
	s_and_b32 s3, s3, 0x60
	s_add_i32 m0, s43, 0x18000
	v_lshl_add_u64 v[4:5], v[4:5], 0, s[28:29]
	v_lshl_add_u64 v[14:15], s[0:1], 0, v[136:137]
	v_mov_b32_e32 v133, v2
	v_bitop3_b32 v21, v18, s10, v3 bitop3:0xde
	s_lshl_b32 s10, s3, 7
	global_load_lds_dwordx4 v[4:5], off
	v_lshl_add_u64 v[4:5], v[6:7], 0, s[28:29]
	s_add_i32 m0, s43, 0x1a000
	s_add_i32 s49, s43, 0x8000
	s_add_i32 s50, s43, 0xa000
	v_lshl_add_u64 v[16:17], s[0:1], 0, v[132:133]
	v_bitop3_b32 v3, v18, s10, v3 bitop3:0xde
	global_load_lds_dwordx4 v[4:5], off
	v_lshl_add_u64 v[4:5], v[14:15], 0, s[28:29]
	s_mov_b32 m0, s49
	s_add_u32 s10, s6, 0x80080
	global_load_lds_dwordx4 v[4:5], off
	v_lshl_add_u64 v[4:5], v[16:17], 0, s[28:29]
	s_mov_b32 m0, s50
	s_addc_u32 s11, s7, 0
	global_load_lds_dwordx4 v[4:5], off
	s_add_i32 m0, s43, 0x1c000
	v_lshl_add_u64 v[4:5], s[10:11], 0, v[134:135]
	global_load_lds_dwordx4 v[4:5], off
	v_lshl_add_u64 v[4:5], s[10:11], 0, v[0:1]
	s_add_i32 m0, s43, 0x1e000
	s_cmpk_lt_u32 s2, 0x100
	global_load_lds_dwordx4 v[4:5], off
	v_lshlrev_b32_e32 v4, 15, v12
	v_and_b32_e32 v4, 0xffff0000, v4
	v_readlane_b32 s2, v250, 59
	v_lshl_add_u32 v4, v11, 12, v4
	v_and_b32_e32 v5, 1, v12
	v_add_u32_e32 v148, s2, v19
	v_or_b32_e32 v149, s3, v20
	v_lshl_or_b32 v4, v5, 6, v4
	v_readlane_b32 s2, v247, 10
	v_lshl_add_u32 v4, v13, 1, v4
	v_mov_b32_e32 v5, v2
	v_readlane_b32 s3, v247, 11
	s_waitcnt vmcnt(8)
	s_barrier
	s_waitcnt vmcnt(6)
	s_cselect_b64 s[10:11], -1, 0
	v_cvt_f32_u32_e32 v188, v173
	v_cvt_f32_u32_e32 v189, v172
	v_fmac_f32_e32 v188, 0x2f800000, v189
	v_fmamk_f32 v188, v188, 0x3a000000, v205
	v_rsq_f32_e32 v240, v188
	v_cvt_f32_u32_e32 v188, v175
	v_cvt_f32_u32_e32 v189, v174
	v_fmac_f32_e32 v188, 0x2f800000, v189
	v_fmamk_f32 v188, v188, 0x3a000000, v205
	v_rsq_f32_e32 v241, v188
	v_cvt_f32_u32_e32 v188, v177
	v_cvt_f32_u32_e32 v189, v176
	v_fmac_f32_e32 v188, 0x2f800000, v189
	v_fmamk_f32 v188, v188, 0x3a000000, v205
	v_rsq_f32_e32 v242, v188
	v_cvt_f32_u32_e32 v188, v179
	v_cvt_f32_u32_e32 v189, v178
	v_fmac_f32_e32 v188, 0x2f800000, v189
	v_fmamk_f32 v188, v188, 0x3a000000, v205
	v_rsq_f32_e32 v243, v188
	v_cvt_f32_u32_e32 v188, v181
	v_cvt_f32_u32_e32 v189, v180
	v_fmac_f32_e32 v188, 0x2f800000, v189
	v_fmamk_f32 v188, v188, 0x3a000000, v205
	v_rsq_f32_e32 v244, v188
	v_cvt_f32_u32_e32 v188, v183
	v_cvt_f32_u32_e32 v189, v182
	v_fmac_f32_e32 v188, 0x2f800000, v189
	v_fmamk_f32 v188, v188, 0x3a000000, v205
	v_rsq_f32_e32 v245, v188
	v_cvt_f32_u32_e32 v188, v185
	v_cvt_f32_u32_e32 v189, v184
	v_fmac_f32_e32 v188, 0x2f800000, v189
	v_fmamk_f32 v188, v188, 0x3a000000, v205
	v_rsq_f32_e32 v246, v188
	v_cvt_f32_u32_e32 v188, v187
	v_cvt_f32_u32_e32 v189, v186
	v_fmac_f32_e32 v188, 0x2f800000, v189
	v_fmamk_f32 v188, v188, 0x3a000000, v205
	v_rsq_f32_e32 v252, v188
	s_nop 0
	s_mov_b32 s51, 0
	v_lshl_add_u64 v[138:139], s[2:3], 0, v[4:5]
	v_lshlrev_b32_e32 v4, 15, v8
	v_and_b32_e32 v4, 0xffff0000, v4
	v_lshl_add_u32 v4, v9, 12, v4
	v_and_b32_e32 v5, 1, v8
	v_lshl_or_b32 v4, v5, 6, v4
	v_lshl_add_u32 v4, v10, 1, v4
	v_mov_b32_e32 v5, v2
	v_lshl_add_u64 v[140:141], s[2:3], 0, v[4:5]
	v_add_u32_e32 v150, 0, v21
	v_readlane_b32 s12, v248, 29
	s_barrier
	v_readlane_b32 s13, v248, 30
	s_branch .LBB0_1050

; #define PG8_STAGE(bufoff, gbase, voff) do { _Pragma("unroll") for (int _i = 0; _i < 2; ++_i) \
;         __builtin_amdgcn_global_load_lds((const unsigned*)((const char*)(gbase) + (voff)[_i]), (PG8_LAS unsigned*)(lds + (bufoff) + ldsw + _i * 8192), 16, 0, 0); } while (0)
; #define PG8_WAIT_V(n) asm volatile("s_waitcnt vmcnt(" #n ")" ::: "memory")
; #define PG8_BAR __builtin_amdgcn_s_barrier()
; template <class Epi, class Sched, bool ALIGN_EPI = false, bool SP2 = false>
; __device__ __forceinline__ void gemm_phase(PG8_LAS unsigned char* lds, const Gemm g, const Sched& S, const Epi& E) {
;     ...
;         PG8_STAGE(PG8_SB(0, 0), cB, voffB); PG8_STAGE(PG8_SB(0, 1), cB + hstep, voffB); PG8_STAGE(PG8_SA(0, 0), cA, voffA); PG8_STAGE(PG8_SA(0, 1), cA + hstep, voffA);
;         if (wr == 1) PG8_BAR;
;         PG8_WAIT_V(2); PG8_BAR;
;         PG8_STAGE(PG8_SB(1, 0), cB + kstep, voffB); PG8_STAGE(PG8_SA(1, 0), cA + kstep, voffA); PG8_STAGE(PG8_SB(1, 1), cB + hstep + kstep, voffB);
;         PG8_WAIT_V(6); PG8_BAR;
.LBB0_1272:
	v_bfe_u32 v21, v3, 4, 2
	s_lshl_b32 s13, s13, 5
	v_mov_b32_e32 v177, v2
	v_and_b32_e32 v20, 15, v3
	v_lshlrev_b32_e32 v23, 4, v21
	v_lshlrev_b32_e32 v3, 2, v3
	s_and_b32 s38, s13, 0x60
	s_add_i32 m0, s49, 0x18000
	v_lshl_add_u64 v[4:5], v[4:5], 0, s[28:29]
	v_lshl_add_u64 v[16:17], s[34:35], 0, v[176:177]
	v_mov_b32_e32 v173, v2
	v_lshl_or_b32 v22, s14, 6, v20
	v_lshl_or_b32 v20, v20, 6, v23
	s_lshl_b32 s14, s14, 13
	v_and_b32_e32 v3, 32, v3
	s_lshl_b32 s13, s38, 7
	global_load_lds_dwordx4 v[4:5], off
	v_lshl_add_u64 v[4:5], v[6:7], 0, s[28:29]
	s_add_i32 m0, s49, 0x1a000
	s_add_i32 s53, s49, 0x8000
	s_add_i32 s57, s49, 0xa000
	v_lshl_add_u64 v[18:19], s[34:35], 0, v[172:173]
	v_bitop3_b32 v23, v20, s14, v3 bitop3:0xde
	global_load_lds_dwordx4 v[4:5], off
	v_lshl_add_u64 v[4:5], v[16:17], 0, s[28:29]
	s_mov_b32 m0, s53
	s_add_u32 s14, s2, 0x160080
	global_load_lds_dwordx4 v[4:5], off
	v_lshl_add_u64 v[4:5], v[18:19], 0, s[28:29]
	s_mov_b32 m0, s57
	s_addc_u32 s15, s3, 0
	global_load_lds_dwordx4 v[4:5], off
	s_add_i32 m0, s49, 0x1c000
	v_lshl_add_u64 v[4:5], s[14:15], 0, v[174:175]
	global_load_lds_dwordx4 v[4:5], off
	v_lshl_add_u64 v[4:5], s[14:15], 0, v[0:1]
	s_add_i32 m0, s49, 0x1e000
	s_movk_i32 s19, 0x1600
	global_load_lds_dwordx4 v[4:5], off
	v_lshrrev_b32_e32 v5, 1, v13
	v_mul_lo_u32 v4, v12, s19
	s_mov_b32 s18, 0x16000
	v_lshl_or_b32 v213, v21, 3, s38
	v_mad_u64_u32 v[4:5], s[38:39], v5, s18, v[4:5]
	v_or_b32_e32 v4, v4, v14
	v_readlane_b32 s16, v247, 20
	v_add_lshl_u32 v4, v4, v15, 1
	v_mov_b32_e32 v5, v2
	v_readlane_b32 s17, v247, 21
	s_cmpk_lt_u32 s12, 0x100
	v_bitop3_b32 v3, v20, s13, v3 bitop3:0xde
	v_lshl_add_u64 v[178:179], s[16:17], 0, v[4:5]
	v_lshrrev_b32_e32 v5, 1, v8
	v_mul_lo_u32 v4, v9, s19
	v_mad_u64_u32 v[4:5], s[38:39], v5, s18, v[4:5]
	v_or_b32_e32 v4, v4, v10
	s_waitcnt vmcnt(8)
	s_barrier
	s_waitcnt vmcnt(6)
	s_cselect_b64 s[12:13], -1, 0
	v_readlane_b32 s14, v250, 59
	s_cmp_eq_u64 s[6:7], 0
	v_add_lshl_u32 v4, v4, v11, 1
	v_mov_b32_e32 v5, v2
	v_add_u32_e32 v212, s14, v22
	s_cselect_b64 s[14:15], -1, 0
	s_cmp_lg_u64 s[6:7], 0
	v_lshl_add_u64 v[180:181], s[16:17], 0, v[4:5]
	v_readlane_b32 s16, v248, 25
	s_mov_b32 s58, 0
	v_cmp_eq_u32_e64 s[36:37], 0, v21
	s_cselect_b64 s[40:41], -1, 0
	v_add_u32_e32 v214, 0, v23
	s_mov_b32 s60, s16
	s_mov_b64 s[42:43], s[2:3]
	s_barrier
	v_readlane_b32 s17, v248, 26
	s_branch .LBB0_1275
